# post: gate-matmul weight fragments preloaded (no per-fragment vmcnt(0)); post token section rewritten wave=token row, lane=4 channels
# speedup vs baseline: 1.0718x; 1.0056x over previous
.LBB0_219:
	s_or_b64 exec, exec, s[18:19]
	s_nop 3
	v_add_u32_e32 v0, s41, v48
	v_ashrrev_i32_e32 v1, 31, v0
	v_readlane_b32 s52, v253, 62
	v_lshlrev_b64 v[2:3], 2, v[0:1]
	v_readlane_b32 s66, v254, 12
	v_readlane_b32 s67, v254, 13
	s_ashr_i32 s17, s16, 31
	v_ashrrev_i32_e32 v49, 31, v48
	v_lshl_add_u64 v[0:1], s[66:67], 0, v[2:3]
	s_lshl_b64 s[18:19], s[16:17], 8
	s_waitcnt lgkmcnt(0)
	s_barrier
	v_readlane_b32 s34, v254, 34
	v_readlane_b32 s44, v254, 30
	v_readlane_b32 s45, v254, 31
	s_sub_u32 s44, s44, 0x110
	s_subb_u32 s45, s45, 0
	s_load_dwordx4 s[52:55], s[44:45], 0xb8
	s_load_dwordx2 s[56:57], s[44:45], 0xd8
	v_readlane_b32 s36, v254, 43
	v_readlane_b32 s37, v254, 44
	v_readfirstlane_b32 s18, v160
	s_lshr_b32 s18, s18, 6
	s_and_b32 s18, s18, 3
	s_mul_i32 s66, s40, 20
	s_add_i32 s66, s66, s18
	s_lshl_b32 s18, s18, 10
	s_add_i32 s18, s18, s47
	s_addk_i32 s18, 0x2200
	v_and_b32_e32 v250, 63, v160
	v_lshlrev_b32_e32 v251, 4, v250
	v_lshlrev_b32_e32 v250, 3, v250
	v_add_u32_e32 v249, s18, v251
	s_lshl_b32 s35, s34, 10
	s_waitcnt lgkmcnt(0)
	s_add_u32 s52, s52, s35
	s_addc_u32 s53, s53, 0
	s_add_u32 s54, s54, s35
	s_addc_u32 s55, s55, 0
	s_add_u32 s56, s56, s35
	s_addc_u32 s57, s57, 0
	global_load_dwordx4 v[190:193], v251, s[52:53]
	global_load_dwordx4 v[194:197], v251, s[54:55]
	global_load_dwordx4 v[198:201], v251, s[56:57]
	s_add_u32 s52, s36, 0x126ca000
	s_addc_u32 s53, s37, 0
	s_add_u32 s54, s36, 0x130ca000
	s_addc_u32 s55, s37, 0
	s_add_u32 s56, s36, 0x13fca000
	s_addc_u32 s57, s37, 0
	s_add_u32 s58, s36, 0x149ca000
	s_addc_u32 s59, s37, 0
	s_add_u32 s60, s36, 0x13aca000
	s_addc_u32 s61, s37, 0
	s_add_u32 s62, s36, 0x664b300
	s_addc_u32 s63, s37, 0
	s_add_u32 s64, s36, 0x153ca000
	s_addc_u32 s65, s37, 0
	s_add_i32 s67, s66, 0
	s_lshl_b32 s18, s67, 10
	s_lshl_b32 s19, s67, 9
	s_mul_i32 s28, s67, 0x1d00
	s_lshl_b32 s29, s67, 11
	v_add_u32_e32 v20, s18, v251
	v_add_u32_e32 v21, s19, v250
	v_add_u32_e32 v22, s28, v250
	v_add_u32_e32 v23, s29, v250
	global_load_dwordx4 v[0:3], v20, s[52:53]
	global_load_dwordx4 v[4:7], v20, s[54:55]
	global_load_dwordx4 v[8:11], v20, s[56:57]
	global_load_dwordx4 v[12:15], v20, s[58:59]
	global_load_dwordx2 v[16:17], v21, s[60:61]
	global_load_dwordx2 v[18:19], v22, s[62:63]
	s_add_i32 s67, s66, 4
	s_lshl_b32 s18, s67, 10
	s_lshl_b32 s19, s67, 9
	s_mul_i32 s28, s67, 0x1d00
	s_lshl_b32 s29, s67, 11
	v_add_u32_e32 v44, s18, v251
	v_add_u32_e32 v45, s19, v250
	v_add_u32_e32 v46, s28, v250
	v_add_u32_e32 v47, s29, v250
	global_load_dwordx4 v[24:27], v44, s[52:53]
	global_load_dwordx4 v[28:31], v44, s[54:55]
	global_load_dwordx4 v[32:35], v44, s[56:57]
	global_load_dwordx4 v[36:39], v44, s[58:59]
	global_load_dwordx2 v[40:41], v45, s[60:61]
	global_load_dwordx2 v[42:43], v46, s[62:63]
	s_add_i32 s67, s66, 8
	s_lshl_b32 s18, s67, 10
	s_lshl_b32 s19, s67, 9
	s_mul_i32 s28, s67, 0x1d00
	s_lshl_b32 s29, s67, 11
	v_add_u32_e32 v68, s18, v251
	v_add_u32_e32 v69, s19, v250
	v_add_u32_e32 v70, s28, v250
	v_add_u32_e32 v71, s29, v250
	global_load_dwordx4 v[48:51], v68, s[52:53]
	global_load_dwordx4 v[52:55], v68, s[54:55]
	global_load_dwordx4 v[56:59], v68, s[56:57]
	global_load_dwordx4 v[60:63], v68, s[58:59]
	global_load_dwordx2 v[64:65], v69, s[60:61]
	global_load_dwordx2 v[66:67], v70, s[62:63]
	ds_read_b128 v[72:75], v249 offset:0
	ds_read_b128 v[76:79], v249 offset:4096
	s_waitcnt vmcnt(18)
	s_waitcnt vmcnt(12)
	v_add_f32_e32 v0, v0, v4
	v_add_f32_e32 v1, v1, v5
	v_add_f32_e32 v2, v2, v6
	v_add_f32_e32 v3, v3, v7
	v_add_f32_e32 v8, v8, v12
	v_add_f32_e32 v9, v9, v13
	v_add_f32_e32 v10, v10, v14
	v_add_f32_e32 v11, v11, v15
	v_add_f32_e32 v84, v0, v1
	v_mul_f32_e32 v86, v8, v8
	v_add_f32_e32 v84, v84, v2
	v_fmac_f32_e32 v86, v9, v9
	v_add_f32_e32 v84, v84, v3
	v_fmac_f32_e32 v86, v10, v10
	v_fmac_f32_e32 v86, v11, v11
	v_lshlrev_b32_e32 v82, 16, v18
	v_and_b32_e32 v18, 0xffff0000, v18
	v_add_f32_dpp v84, v84, v84 quad_perm:[1,0,3,2] row_mask:0xf bank_mask:0xf bound_ctrl:1
	v_add_f32_dpp v86, v86, v86 quad_perm:[1,0,3,2] row_mask:0xf bank_mask:0xf bound_ctrl:1
	v_lshlrev_b32_e32 v83, 16, v19
	v_and_b32_e32 v19, 0xffff0000, v19
	v_add_f32_dpp v84, v84, v84 quad_perm:[2,3,0,1] row_mask:0xf bank_mask:0xf bound_ctrl:1
	v_add_f32_dpp v86, v86, v86 quad_perm:[2,3,0,1] row_mask:0xf bank_mask:0xf bound_ctrl:1
	v_mul_f32_e32 v82, 0xbfb8aa3b, v82
	v_mul_f32_e32 v18, 0xbfb8aa3b, v18
	v_add_f32_dpp v84, v84, v84 row_half_mirror row_mask:0xf bank_mask:0xf bound_ctrl:1
	v_add_f32_dpp v86, v86, v86 row_half_mirror row_mask:0xf bank_mask:0xf bound_ctrl:1
	v_mul_f32_e32 v83, 0xbfb8aa3b, v83
	v_mul_f32_e32 v19, 0xbfb8aa3b, v19
	v_add_f32_dpp v84, v84, v84 row_mirror row_mask:0xf bank_mask:0xf bound_ctrl:1
	v_add_f32_dpp v86, v86, v86 row_mirror row_mask:0xf bank_mask:0xf bound_ctrl:1
	v_exp_f32_e32 v82, v82
	v_exp_f32_e32 v18, v18
	v_exp_f32_e32 v83, v83
	v_exp_f32_e32 v19, v19
	v_fmac_f32_e32 v0, 0xbc800000, v84
	v_fmac_f32_e32 v1, 0xbc800000, v84
	v_fmac_f32_e32 v2, 0xbc800000, v84
	v_fmac_f32_e32 v3, 0xbc800000, v84
	v_mul_f32_e32 v85, v0, v0
	v_fmac_f32_e32 v85, v1, v1
	v_fmac_f32_e32 v85, v2, v2
	v_fmac_f32_e32 v85, v3, v3
	v_add_f32_e32 v82, 1.0, v82
	v_add_f32_e32 v18, 1.0, v18
	v_add_f32_dpp v85, v85, v85 quad_perm:[1,0,3,2] row_mask:0xf bank_mask:0xf bound_ctrl:1
	v_add_f32_e32 v83, 1.0, v83
	v_add_f32_e32 v19, 1.0, v19
	v_add_f32_dpp v85, v85, v85 quad_perm:[2,3,0,1] row_mask:0xf bank_mask:0xf bound_ctrl:1
	v_rcp_f32_e32 v82, v82
	v_rcp_f32_e32 v18, v18
	v_add_f32_dpp v85, v85, v85 row_half_mirror row_mask:0xf bank_mask:0xf bound_ctrl:1
	v_rcp_f32_e32 v83, v83
	v_rcp_f32_e32 v19, v19
	v_add_f32_dpp v85, v85, v85 row_mirror row_mask:0xf bank_mask:0xf bound_ctrl:1
	v_lshlrev_b32_e32 v80, 16, v16
	v_and_b32_e32 v16, 0xffff0000, v16
	v_lshlrev_b32_e32 v81, 16, v17
	v_and_b32_e32 v17, 0xffff0000, v17
	v_fmamk_f32 v86, v86, 0x3c800000, v161
	v_rsq_f32_e32 v88, v86
	v_fmamk_f32 v85, v85, 0x3c800000, v162
	v_rsq_f32_e32 v87, v85
	v_mul_f32_e32 v8, v8, v88
	v_mul_f32_e32 v9, v9, v88
	v_mul_f32_e32 v10, v10, v88
	v_mul_f32_e32 v11, v11, v88
	v_mul_f32_e32 v8, v198, v8
	v_mul_f32_e32 v9, v199, v9
	v_mul_f32_e32 v10, v200, v10
	v_mul_f32_e32 v11, v201, v11
	v_mul_f32_e32 v8, v82, v8
	v_mul_f32_e32 v9, v18, v9
	v_mul_f32_e32 v10, v83, v10
	v_mul_f32_e32 v11, v19, v11
	s_waitcnt lgkmcnt(1)
	v_mul_f32_e32 v0, v0, v87
	v_mul_f32_e32 v1, v1, v87
	v_mul_f32_e32 v2, v2, v87
	v_mul_f32_e32 v3, v3, v87
	v_fma_f32 v0, v190, v0, v194
	v_fma_f32 v1, v191, v1, v195
	v_fma_f32 v2, v192, v2, v196
	v_fma_f32 v3, v193, v3, v197
	v_add_f32_e32 v0, v0, v80
	v_add_f32_e32 v1, v1, v16
	v_add_f32_e32 v2, v2, v81
	v_add_f32_e32 v3, v3, v17
	v_mul_f32_e32 v0, v72, v0
	v_mul_f32_e32 v1, v73, v1
	v_mul_f32_e32 v2, v74, v2
	v_mul_f32_e32 v3, v75, v3
	v_cvt_pk_bf16_f32 v202, v0, v1
	v_cvt_pk_bf16_f32 v203, v2, v3
	global_store_dwordx2 v23, v[202:203], s[64:65]
	v_cvt_pk_bf16_f32 v204, v8, v9
	v_cvt_pk_bf16_f32 v205, v10, v11
	global_store_dwordx2 v23, v[204:205], s[64:65] offset:1024
	s_add_i32 s67, s66, 12
	s_lshl_b32 s18, s67, 10
	s_lshl_b32 s19, s67, 9
	s_mul_i32 s28, s67, 0x1d00
	s_lshl_b32 s29, s67, 11
	v_add_u32_e32 v20, s18, v251
	v_add_u32_e32 v21, s19, v250
	v_add_u32_e32 v22, s28, v250
	v_add_u32_e32 v23, s29, v250
	global_load_dwordx4 v[0:3], v20, s[52:53]
	global_load_dwordx4 v[4:7], v20, s[54:55]
	global_load_dwordx4 v[8:11], v20, s[56:57]
	global_load_dwordx4 v[12:15], v20, s[58:59]
	global_load_dwordx2 v[16:17], v21, s[60:61]
	global_load_dwordx2 v[18:19], v22, s[62:63]
	ds_read_b128 v[72:75], v249 offset:8192
	s_waitcnt vmcnt(14)
	v_add_f32_e32 v24, v24, v28
	v_add_f32_e32 v25, v25, v29
	v_add_f32_e32 v26, v26, v30
	v_add_f32_e32 v27, v27, v31
	v_add_f32_e32 v32, v32, v36
	v_add_f32_e32 v33, v33, v37
	v_add_f32_e32 v34, v34, v38
	v_add_f32_e32 v35, v35, v39
	v_add_f32_e32 v84, v24, v25
	v_mul_f32_e32 v86, v32, v32
	v_add_f32_e32 v84, v84, v26
	v_fmac_f32_e32 v86, v33, v33
	v_add_f32_e32 v84, v84, v27
	v_fmac_f32_e32 v86, v34, v34
	v_fmac_f32_e32 v86, v35, v35
	v_lshlrev_b32_e32 v82, 16, v42
	v_and_b32_e32 v42, 0xffff0000, v42
	v_add_f32_dpp v84, v84, v84 quad_perm:[1,0,3,2] row_mask:0xf bank_mask:0xf bound_ctrl:1
	v_add_f32_dpp v86, v86, v86 quad_perm:[1,0,3,2] row_mask:0xf bank_mask:0xf bound_ctrl:1
	v_lshlrev_b32_e32 v83, 16, v43
	v_and_b32_e32 v43, 0xffff0000, v43
	v_add_f32_dpp v84, v84, v84 quad_perm:[2,3,0,1] row_mask:0xf bank_mask:0xf bound_ctrl:1
	v_add_f32_dpp v86, v86, v86 quad_perm:[2,3,0,1] row_mask:0xf bank_mask:0xf bound_ctrl:1
	v_mul_f32_e32 v82, 0xbfb8aa3b, v82
	v_mul_f32_e32 v42, 0xbfb8aa3b, v42
	v_add_f32_dpp v84, v84, v84 row_half_mirror row_mask:0xf bank_mask:0xf bound_ctrl:1
	v_add_f32_dpp v86, v86, v86 row_half_mirror row_mask:0xf bank_mask:0xf bound_ctrl:1
	v_mul_f32_e32 v83, 0xbfb8aa3b, v83
	v_mul_f32_e32 v43, 0xbfb8aa3b, v43
	v_add_f32_dpp v84, v84, v84 row_mirror row_mask:0xf bank_mask:0xf bound_ctrl:1
	v_add_f32_dpp v86, v86, v86 row_mirror row_mask:0xf bank_mask:0xf bound_ctrl:1
	v_exp_f32_e32 v82, v82
	v_exp_f32_e32 v42, v42
	v_exp_f32_e32 v83, v83
	v_exp_f32_e32 v43, v43
	v_fmac_f32_e32 v24, 0xbc800000, v84
	v_fmac_f32_e32 v25, 0xbc800000, v84
	v_fmac_f32_e32 v26, 0xbc800000, v84
	v_fmac_f32_e32 v27, 0xbc800000, v84
	v_mul_f32_e32 v85, v24, v24
	v_fmac_f32_e32 v85, v25, v25
	v_fmac_f32_e32 v85, v26, v26
	v_fmac_f32_e32 v85, v27, v27
	v_add_f32_e32 v82, 1.0, v82
	v_add_f32_e32 v42, 1.0, v42
	v_add_f32_dpp v85, v85, v85 quad_perm:[1,0,3,2] row_mask:0xf bank_mask:0xf bound_ctrl:1
	v_add_f32_e32 v83, 1.0, v83
	v_add_f32_e32 v43, 1.0, v43
	v_add_f32_dpp v85, v85, v85 quad_perm:[2,3,0,1] row_mask:0xf bank_mask:0xf bound_ctrl:1
	v_rcp_f32_e32 v82, v82
	v_rcp_f32_e32 v42, v42
	v_add_f32_dpp v85, v85, v85 row_half_mirror row_mask:0xf bank_mask:0xf bound_ctrl:1
	v_rcp_f32_e32 v83, v83
	v_rcp_f32_e32 v43, v43
	v_add_f32_dpp v85, v85, v85 row_mirror row_mask:0xf bank_mask:0xf bound_ctrl:1
	v_lshlrev_b32_e32 v80, 16, v40
	v_and_b32_e32 v40, 0xffff0000, v40
	v_lshlrev_b32_e32 v81, 16, v41
	v_and_b32_e32 v41, 0xffff0000, v41
	v_fmamk_f32 v86, v86, 0x3c800000, v161
	v_rsq_f32_e32 v88, v86
	v_fmamk_f32 v85, v85, 0x3c800000, v162
	v_rsq_f32_e32 v87, v85
	v_mul_f32_e32 v32, v32, v88
	v_mul_f32_e32 v33, v33, v88
	v_mul_f32_e32 v34, v34, v88
	v_mul_f32_e32 v35, v35, v88
	v_mul_f32_e32 v32, v198, v32
	v_mul_f32_e32 v33, v199, v33
	v_mul_f32_e32 v34, v200, v34
	v_mul_f32_e32 v35, v201, v35
	v_mul_f32_e32 v32, v82, v32
	v_mul_f32_e32 v33, v42, v33
	v_mul_f32_e32 v34, v83, v34
	v_mul_f32_e32 v35, v43, v35
	s_waitcnt lgkmcnt(1)
	v_mul_f32_e32 v24, v24, v87
	v_mul_f32_e32 v25, v25, v87
	v_mul_f32_e32 v26, v26, v87
	v_mul_f32_e32 v27, v27, v87
	v_fma_f32 v24, v190, v24, v194
	v_fma_f32 v25, v191, v25, v195
	v_fma_f32 v26, v192, v26, v196
	v_fma_f32 v27, v193, v27, v197
	v_add_f32_e32 v24, v24, v80
	v_add_f32_e32 v25, v25, v40
	v_add_f32_e32 v26, v26, v81
	v_add_f32_e32 v27, v27, v41
	v_mul_f32_e32 v24, v76, v24
	v_mul_f32_e32 v25, v77, v25
	v_mul_f32_e32 v26, v78, v26
	v_mul_f32_e32 v27, v79, v27
	v_cvt_pk_bf16_f32 v202, v24, v25
	v_cvt_pk_bf16_f32 v203, v26, v27
	global_store_dwordx2 v47, v[202:203], s[64:65]
	v_cvt_pk_bf16_f32 v204, v32, v33
	v_cvt_pk_bf16_f32 v205, v34, v35
	global_store_dwordx2 v47, v[204:205], s[64:65] offset:1024
	s_add_i32 s67, s66, 16
	s_lshl_b32 s18, s67, 10
	s_lshl_b32 s19, s67, 9
	s_mul_i32 s28, s67, 0x1d00
	s_lshl_b32 s29, s67, 11
	v_add_u32_e32 v44, s18, v251
	v_add_u32_e32 v45, s19, v250
	v_add_u32_e32 v46, s28, v250
	v_add_u32_e32 v47, s29, v250
	global_load_dwordx4 v[24:27], v44, s[52:53]
	global_load_dwordx4 v[28:31], v44, s[54:55]
	global_load_dwordx4 v[32:35], v44, s[56:57]
	global_load_dwordx4 v[36:39], v44, s[58:59]
	global_load_dwordx2 v[40:41], v45, s[60:61]
	global_load_dwordx2 v[42:43], v46, s[62:63]
	ds_read_b128 v[76:79], v249 offset:12288
	s_waitcnt vmcnt(16)
	v_add_f32_e32 v48, v48, v52
	v_add_f32_e32 v49, v49, v53
	v_add_f32_e32 v50, v50, v54
	v_add_f32_e32 v51, v51, v55
	v_add_f32_e32 v56, v56, v60
	v_add_f32_e32 v57, v57, v61
	v_add_f32_e32 v58, v58, v62
	v_add_f32_e32 v59, v59, v63
	v_add_f32_e32 v84, v48, v49
	v_mul_f32_e32 v86, v56, v56
	v_add_f32_e32 v84, v84, v50
	v_fmac_f32_e32 v86, v57, v57
	v_add_f32_e32 v84, v84, v51
	v_fmac_f32_e32 v86, v58, v58
	v_fmac_f32_e32 v86, v59, v59
	v_lshlrev_b32_e32 v82, 16, v66
	v_and_b32_e32 v66, 0xffff0000, v66
	v_add_f32_dpp v84, v84, v84 quad_perm:[1,0,3,2] row_mask:0xf bank_mask:0xf bound_ctrl:1
	v_add_f32_dpp v86, v86, v86 quad_perm:[1,0,3,2] row_mask:0xf bank_mask:0xf bound_ctrl:1
	v_lshlrev_b32_e32 v83, 16, v67
	v_and_b32_e32 v67, 0xffff0000, v67
	v_add_f32_dpp v84, v84, v84 quad_perm:[2,3,0,1] row_mask:0xf bank_mask:0xf bound_ctrl:1
	v_add_f32_dpp v86, v86, v86 quad_perm:[2,3,0,1] row_mask:0xf bank_mask:0xf bound_ctrl:1
	v_mul_f32_e32 v82, 0xbfb8aa3b, v82
	v_mul_f32_e32 v66, 0xbfb8aa3b, v66
	v_add_f32_dpp v84, v84, v84 row_half_mirror row_mask:0xf bank_mask:0xf bound_ctrl:1
	v_add_f32_dpp v86, v86, v86 row_half_mirror row_mask:0xf bank_mask:0xf bound_ctrl:1
	v_mul_f32_e32 v83, 0xbfb8aa3b, v83
	v_mul_f32_e32 v67, 0xbfb8aa3b, v67
	v_add_f32_dpp v84, v84, v84 row_mirror row_mask:0xf bank_mask:0xf bound_ctrl:1
	v_add_f32_dpp v86, v86, v86 row_mirror row_mask:0xf bank_mask:0xf bound_ctrl:1
	v_exp_f32_e32 v82, v82
	v_exp_f32_e32 v66, v66
	v_exp_f32_e32 v83, v83
	v_exp_f32_e32 v67, v67
	v_fmac_f32_e32 v48, 0xbc800000, v84
	v_fmac_f32_e32 v49, 0xbc800000, v84
	v_fmac_f32_e32 v50, 0xbc800000, v84
	v_fmac_f32_e32 v51, 0xbc800000, v84
	v_mul_f32_e32 v85, v48, v48
	v_fmac_f32_e32 v85, v49, v49
	v_fmac_f32_e32 v85, v50, v50
	v_fmac_f32_e32 v85, v51, v51
	v_add_f32_e32 v82, 1.0, v82
	v_add_f32_e32 v66, 1.0, v66
	v_add_f32_dpp v85, v85, v85 quad_perm:[1,0,3,2] row_mask:0xf bank_mask:0xf bound_ctrl:1
	v_add_f32_e32 v83, 1.0, v83
	v_add_f32_e32 v67, 1.0, v67
	v_add_f32_dpp v85, v85, v85 quad_perm:[2,3,0,1] row_mask:0xf bank_mask:0xf bound_ctrl:1
	v_rcp_f32_e32 v82, v82
	v_rcp_f32_e32 v66, v66
	v_add_f32_dpp v85, v85, v85 row_half_mirror row_mask:0xf bank_mask:0xf bound_ctrl:1
	v_rcp_f32_e32 v83, v83
	v_rcp_f32_e32 v67, v67
	v_add_f32_dpp v85, v85, v85 row_mirror row_mask:0xf bank_mask:0xf bound_ctrl:1
	v_lshlrev_b32_e32 v80, 16, v64
	v_and_b32_e32 v64, 0xffff0000, v64
	v_lshlrev_b32_e32 v81, 16, v65
	v_and_b32_e32 v65, 0xffff0000, v65
	v_fmamk_f32 v86, v86, 0x3c800000, v161
	v_rsq_f32_e32 v88, v86
	v_fmamk_f32 v85, v85, 0x3c800000, v162
	v_rsq_f32_e32 v87, v85
	v_mul_f32_e32 v56, v56, v88
	v_mul_f32_e32 v57, v57, v88
	v_mul_f32_e32 v58, v58, v88
	v_mul_f32_e32 v59, v59, v88
	v_mul_f32_e32 v56, v198, v56
	v_mul_f32_e32 v57, v199, v57
	v_mul_f32_e32 v58, v200, v58
	v_mul_f32_e32 v59, v201, v59
	v_mul_f32_e32 v56, v82, v56
	v_mul_f32_e32 v57, v66, v57
	v_mul_f32_e32 v58, v83, v58
	v_mul_f32_e32 v59, v67, v59
	s_waitcnt lgkmcnt(1)
	v_mul_f32_e32 v48, v48, v87
	v_mul_f32_e32 v49, v49, v87
	v_mul_f32_e32 v50, v50, v87
	v_mul_f32_e32 v51, v51, v87
	v_fma_f32 v48, v190, v48, v194
	v_fma_f32 v49, v191, v49, v195
	v_fma_f32 v50, v192, v50, v196
	v_fma_f32 v51, v193, v51, v197
	v_add_f32_e32 v48, v48, v80
	v_add_f32_e32 v49, v49, v64
	v_add_f32_e32 v50, v50, v81
	v_add_f32_e32 v51, v51, v65
	v_mul_f32_e32 v48, v72, v48
	v_mul_f32_e32 v49, v73, v49
	v_mul_f32_e32 v50, v74, v50
	v_mul_f32_e32 v51, v75, v51
	v_cvt_pk_bf16_f32 v202, v48, v49
	v_cvt_pk_bf16_f32 v203, v50, v51
	global_store_dwordx2 v71, v[202:203], s[64:65]
	v_cvt_pk_bf16_f32 v204, v56, v57
	v_cvt_pk_bf16_f32 v205, v58, v59
	global_store_dwordx2 v71, v[204:205], s[64:65] offset:1024
	ds_read_b128 v[72:75], v249 offset:16384
	s_waitcnt vmcnt(10)
	v_add_f32_e32 v0, v0, v4
	v_add_f32_e32 v1, v1, v5
	v_add_f32_e32 v2, v2, v6
	v_add_f32_e32 v3, v3, v7
	v_add_f32_e32 v8, v8, v12
	v_add_f32_e32 v9, v9, v13
	v_add_f32_e32 v10, v10, v14
	v_add_f32_e32 v11, v11, v15
	v_add_f32_e32 v84, v0, v1
	v_mul_f32_e32 v86, v8, v8
	v_add_f32_e32 v84, v84, v2
	v_fmac_f32_e32 v86, v9, v9
	v_add_f32_e32 v84, v84, v3
	v_fmac_f32_e32 v86, v10, v10
	v_fmac_f32_e32 v86, v11, v11
	v_lshlrev_b32_e32 v82, 16, v18
	v_and_b32_e32 v18, 0xffff0000, v18
	v_add_f32_dpp v84, v84, v84 quad_perm:[1,0,3,2] row_mask:0xf bank_mask:0xf bound_ctrl:1
	v_add_f32_dpp v86, v86, v86 quad_perm:[1,0,3,2] row_mask:0xf bank_mask:0xf bound_ctrl:1
	v_lshlrev_b32_e32 v83, 16, v19
	v_and_b32_e32 v19, 0xffff0000, v19
	v_add_f32_dpp v84, v84, v84 quad_perm:[2,3,0,1] row_mask:0xf bank_mask:0xf bound_ctrl:1
	v_add_f32_dpp v86, v86, v86 quad_perm:[2,3,0,1] row_mask:0xf bank_mask:0xf bound_ctrl:1
	v_mul_f32_e32 v82, 0xbfb8aa3b, v82
	v_mul_f32_e32 v18, 0xbfb8aa3b, v18
	v_add_f32_dpp v84, v84, v84 row_half_mirror row_mask:0xf bank_mask:0xf bound_ctrl:1
	v_add_f32_dpp v86, v86, v86 row_half_mirror row_mask:0xf bank_mask:0xf bound_ctrl:1
	v_mul_f32_e32 v83, 0xbfb8aa3b, v83
	v_mul_f32_e32 v19, 0xbfb8aa3b, v19
	v_add_f32_dpp v84, v84, v84 row_mirror row_mask:0xf bank_mask:0xf bound_ctrl:1
	v_add_f32_dpp v86, v86, v86 row_mirror row_mask:0xf bank_mask:0xf bound_ctrl:1
	v_exp_f32_e32 v82, v82
	v_exp_f32_e32 v18, v18
	v_exp_f32_e32 v83, v83
	v_exp_f32_e32 v19, v19
	v_fmac_f32_e32 v0, 0xbc800000, v84
	v_fmac_f32_e32 v1, 0xbc800000, v84
	v_fmac_f32_e32 v2, 0xbc800000, v84
	v_fmac_f32_e32 v3, 0xbc800000, v84
	v_mul_f32_e32 v85, v0, v0
	v_fmac_f32_e32 v85, v1, v1
	v_fmac_f32_e32 v85, v2, v2
	v_fmac_f32_e32 v85, v3, v3
	v_add_f32_e32 v82, 1.0, v82
	v_add_f32_e32 v18, 1.0, v18
	v_add_f32_dpp v85, v85, v85 quad_perm:[1,0,3,2] row_mask:0xf bank_mask:0xf bound_ctrl:1
	v_add_f32_e32 v83, 1.0, v83
	v_add_f32_e32 v19, 1.0, v19
	v_add_f32_dpp v85, v85, v85 quad_perm:[2,3,0,1] row_mask:0xf bank_mask:0xf bound_ctrl:1
	v_rcp_f32_e32 v82, v82
	v_rcp_f32_e32 v18, v18
	v_add_f32_dpp v85, v85, v85 row_half_mirror row_mask:0xf bank_mask:0xf bound_ctrl:1
	v_rcp_f32_e32 v83, v83
	v_rcp_f32_e32 v19, v19
	v_add_f32_dpp v85, v85, v85 row_mirror row_mask:0xf bank_mask:0xf bound_ctrl:1
	v_lshlrev_b32_e32 v80, 16, v16
	v_and_b32_e32 v16, 0xffff0000, v16
	v_lshlrev_b32_e32 v81, 16, v17
	v_and_b32_e32 v17, 0xffff0000, v17
	v_fmamk_f32 v86, v86, 0x3c800000, v161
	v_rsq_f32_e32 v88, v86
	v_fmamk_f32 v85, v85, 0x3c800000, v162
	v_rsq_f32_e32 v87, v85
	v_mul_f32_e32 v8, v8, v88
	v_mul_f32_e32 v9, v9, v88
	v_mul_f32_e32 v10, v10, v88
	v_mul_f32_e32 v11, v11, v88
	v_mul_f32_e32 v8, v198, v8
	v_mul_f32_e32 v9, v199, v9
	v_mul_f32_e32 v10, v200, v10
	v_mul_f32_e32 v11, v201, v11
	v_mul_f32_e32 v8, v82, v8
	v_mul_f32_e32 v9, v18, v9
	v_mul_f32_e32 v10, v83, v10
	v_mul_f32_e32 v11, v19, v11
	s_waitcnt lgkmcnt(1)
	v_mul_f32_e32 v0, v0, v87
	v_mul_f32_e32 v1, v1, v87
	v_mul_f32_e32 v2, v2, v87
	v_mul_f32_e32 v3, v3, v87
	v_fma_f32 v0, v190, v0, v194
	v_fma_f32 v1, v191, v1, v195
	v_fma_f32 v2, v192, v2, v196
	v_fma_f32 v3, v193, v3, v197
	v_add_f32_e32 v0, v0, v80
	v_add_f32_e32 v1, v1, v16
	v_add_f32_e32 v2, v2, v81
	v_add_f32_e32 v3, v3, v17
	v_mul_f32_e32 v0, v76, v0
	v_mul_f32_e32 v1, v77, v1
	v_mul_f32_e32 v2, v78, v2
	v_mul_f32_e32 v3, v79, v3
	v_cvt_pk_bf16_f32 v202, v0, v1
	v_cvt_pk_bf16_f32 v203, v2, v3
	global_store_dwordx2 v23, v[202:203], s[64:65]
	v_cvt_pk_bf16_f32 v204, v8, v9
	v_cvt_pk_bf16_f32 v205, v10, v11
	global_store_dwordx2 v23, v[204:205], s[64:65] offset:1024
	s_waitcnt vmcnt(4)
	v_add_f32_e32 v24, v24, v28
	v_add_f32_e32 v25, v25, v29
	v_add_f32_e32 v26, v26, v30
	v_add_f32_e32 v27, v27, v31
	v_add_f32_e32 v32, v32, v36
	v_add_f32_e32 v33, v33, v37
	v_add_f32_e32 v34, v34, v38
	v_add_f32_e32 v35, v35, v39
	v_add_f32_e32 v84, v24, v25
	v_mul_f32_e32 v86, v32, v32
	v_add_f32_e32 v84, v84, v26
	v_fmac_f32_e32 v86, v33, v33
	v_add_f32_e32 v84, v84, v27
	v_fmac_f32_e32 v86, v34, v34
	v_fmac_f32_e32 v86, v35, v35
	v_lshlrev_b32_e32 v82, 16, v42
	v_and_b32_e32 v42, 0xffff0000, v42
	v_add_f32_dpp v84, v84, v84 quad_perm:[1,0,3,2] row_mask:0xf bank_mask:0xf bound_ctrl:1
	v_add_f32_dpp v86, v86, v86 quad_perm:[1,0,3,2] row_mask:0xf bank_mask:0xf bound_ctrl:1
	v_lshlrev_b32_e32 v83, 16, v43
	v_and_b32_e32 v43, 0xffff0000, v43
	v_add_f32_dpp v84, v84, v84 quad_perm:[2,3,0,1] row_mask:0xf bank_mask:0xf bound_ctrl:1
	v_add_f32_dpp v86, v86, v86 quad_perm:[2,3,0,1] row_mask:0xf bank_mask:0xf bound_ctrl:1
	v_mul_f32_e32 v82, 0xbfb8aa3b, v82
	v_mul_f32_e32 v42, 0xbfb8aa3b, v42
	v_add_f32_dpp v84, v84, v84 row_half_mirror row_mask:0xf bank_mask:0xf bound_ctrl:1
	v_add_f32_dpp v86, v86, v86 row_half_mirror row_mask:0xf bank_mask:0xf bound_ctrl:1
	v_mul_f32_e32 v83, 0xbfb8aa3b, v83
	v_mul_f32_e32 v43, 0xbfb8aa3b, v43
	v_add_f32_dpp v84, v84, v84 row_mirror row_mask:0xf bank_mask:0xf bound_ctrl:1
	v_add_f32_dpp v86, v86, v86 row_mirror row_mask:0xf bank_mask:0xf bound_ctrl:1
	v_exp_f32_e32 v82, v82
	v_exp_f32_e32 v42, v42
	v_exp_f32_e32 v83, v83
	v_exp_f32_e32 v43, v43
	v_fmac_f32_e32 v24, 0xbc800000, v84
	v_fmac_f32_e32 v25, 0xbc800000, v84
	v_fmac_f32_e32 v26, 0xbc800000, v84
	v_fmac_f32_e32 v27, 0xbc800000, v84
	v_mul_f32_e32 v85, v24, v24
	v_fmac_f32_e32 v85, v25, v25
	v_fmac_f32_e32 v85, v26, v26
	v_fmac_f32_e32 v85, v27, v27
	v_add_f32_e32 v82, 1.0, v82
	v_add_f32_e32 v42, 1.0, v42
	v_add_f32_dpp v85, v85, v85 quad_perm:[1,0,3,2] row_mask:0xf bank_mask:0xf bound_ctrl:1
	v_add_f32_e32 v83, 1.0, v83
	v_add_f32_e32 v43, 1.0, v43
	v_add_f32_dpp v85, v85, v85 quad_perm:[2,3,0,1] row_mask:0xf bank_mask:0xf bound_ctrl:1
	v_rcp_f32_e32 v82, v82
	v_rcp_f32_e32 v42, v42
	v_add_f32_dpp v85, v85, v85 row_half_mirror row_mask:0xf bank_mask:0xf bound_ctrl:1
	v_rcp_f32_e32 v83, v83
	v_rcp_f32_e32 v43, v43
	v_add_f32_dpp v85, v85, v85 row_mirror row_mask:0xf bank_mask:0xf bound_ctrl:1
	v_lshlrev_b32_e32 v80, 16, v40
	v_and_b32_e32 v40, 0xffff0000, v40
	v_lshlrev_b32_e32 v81, 16, v41
	v_and_b32_e32 v41, 0xffff0000, v41
	v_fmamk_f32 v86, v86, 0x3c800000, v161
	v_rsq_f32_e32 v88, v86
	v_fmamk_f32 v85, v85, 0x3c800000, v162
	v_rsq_f32_e32 v87, v85
	v_mul_f32_e32 v32, v32, v88
	v_mul_f32_e32 v33, v33, v88
	v_mul_f32_e32 v34, v34, v88
	v_mul_f32_e32 v35, v35, v88
	v_mul_f32_e32 v32, v198, v32
	v_mul_f32_e32 v33, v199, v33
	v_mul_f32_e32 v34, v200, v34
	v_mul_f32_e32 v35, v201, v35
	v_mul_f32_e32 v32, v82, v32
	v_mul_f32_e32 v33, v42, v33
	v_mul_f32_e32 v34, v83, v34
	v_mul_f32_e32 v35, v43, v35
	s_waitcnt lgkmcnt(0)
	v_mul_f32_e32 v24, v24, v87
	v_mul_f32_e32 v25, v25, v87
	v_mul_f32_e32 v26, v26, v87
	v_mul_f32_e32 v27, v27, v87
	v_fma_f32 v24, v190, v24, v194
	v_fma_f32 v25, v191, v25, v195
	v_fma_f32 v26, v192, v26, v196
	v_fma_f32 v27, v193, v27, v197
	v_add_f32_e32 v24, v24, v80
	v_add_f32_e32 v25, v25, v40
	v_add_f32_e32 v26, v26, v81
	v_add_f32_e32 v27, v27, v41
	v_mul_f32_e32 v24, v72, v24
	v_mul_f32_e32 v25, v73, v25
	v_mul_f32_e32 v26, v74, v26
	v_mul_f32_e32 v27, v75, v27
	v_cvt_pk_bf16_f32 v202, v24, v25
	v_cvt_pk_bf16_f32 v203, v26, v27
	global_store_dwordx2 v47, v[202:203], s[64:65]
	v_cvt_pk_bf16_f32 v204, v32, v33
	v_cvt_pk_bf16_f32 v205, v34, v35
	global_store_dwordx2 v47, v[204:205], s[64:65] offset:1024
	v_readlane_b32 s16, v254, 30
	v_readlane_b32 s17, v254, 31
	s_barrier
	s_load_dword s16, s[16:17], 0x0
	s_waitcnt lgkmcnt(0)
	s_lshl_b32 s16, s16, 1
	s_add_i32 s40, s16, s40
	s_cmpk_gt_i32 s40, 0x1ff
	s_cbranch_scc1 .LBB0_224
.LBB0_220:
	v_mov_b32 v0, 0
	s_mul_i32 s16, s40, 20
	v_add_u32_sdwa v48, v0, v160 dst_sel:DWORD dst_unused:UNUSED_PAD src0_sel:DWORD src1_sel:BYTE_0
	v_ashrrev_i32_e32 v5, 7, v48
	v_and_b32_e32 v4, 0x7f, v48
	v_add_u32_e32 v2, s16, v5
	v_mov_b64_e32 v[0:1], s[0:1]
	v_mad_i64_i32 v[2:3], s[18:19], v2, s87, v[0:1]
	v_lshlrev_b32_e32 v128, 1, v4
	v_lshl_add_u64 v[2:3], v[2:3], 0, v[128:129]
	s_waitcnt vmcnt(0) lgkmcnt(0)
	s_barrier
	global_load_ushort v4, v[2:3], off offset:1536
	v_add_u32_e32 v2, 0x100, v48
	v_ashrrev_i32_e32 v6, 7, v2
	v_add_u32_e32 v2, s16, v6
	v_mad_i64_i32 v[2:3], s[18:19], v2, s87, v[0:1]
	v_lshl_add_u64 v[2:3], v[2:3], 0, v[128:129]
	global_load_ushort v7, v[2:3], off offset:1536
	v_add_u32_e32 v2, 0x200, v48
	v_ashrrev_i32_e32 v8, 7, v2
	v_add_u32_e32 v2, s16, v8
	v_mad_i64_i32 v[2:3], s[18:19], v2, s87, v[0:1]
	v_lshl_add_u64 v[2:3], v[2:3], 0, v[128:129]
	global_load_ushort v9, v[2:3], off offset:1536
	v_add_u32_e32 v2, 0x300, v48
	v_ashrrev_i32_e32 v10, 7, v2
	v_add_u32_e32 v2, s16, v10
	v_mad_i64_i32 v[2:3], s[18:19], v2, s87, v[0:1]
	v_lshl_add_u64 v[2:3], v[2:3], 0, v[128:129]
	global_load_ushort v11, v[2:3], off offset:1536
	v_add_u32_e32 v2, 0x400, v48
	v_ashrrev_i32_e32 v12, 7, v2
	v_add_u32_e32 v2, s16, v12
	v_mad_i64_i32 v[2:3], s[18:19], v2, s87, v[0:1]
	v_lshl_add_u64 v[2:3], v[2:3], 0, v[128:129]
	global_load_ushort v13, v[2:3], off offset:1536
	v_add_u32_e32 v2, 0x500, v48
	v_ashrrev_i32_e32 v14, 7, v2
	v_add_u32_e32 v2, s16, v14
	v_mad_i64_i32 v[2:3], s[18:19], v2, s87, v[0:1]
	v_lshl_add_u64 v[2:3], v[2:3], 0, v[128:129]
	global_load_ushort v15, v[2:3], off offset:1536
	v_add_u32_e32 v2, 0x600, v48
	v_ashrrev_i32_e32 v16, 7, v2
	v_add_u32_e32 v2, s16, v16
	v_mad_i64_i32 v[2:3], s[18:19], v2, s87, v[0:1]
	v_lshl_add_u64 v[2:3], v[2:3], 0, v[128:129]
	global_load_ushort v17, v[2:3], off offset:1536
	v_add_u32_e32 v2, 0x700, v48
	v_ashrrev_i32_e32 v18, 7, v2
	v_add_u32_e32 v2, s16, v18
	v_mad_i64_i32 v[2:3], s[18:19], v2, s87, v[0:1]
	v_lshl_add_u64 v[2:3], v[2:3], 0, v[128:129]
	global_load_ushort v19, v[2:3], off offset:1536
	v_add_u32_e32 v2, 0x800, v48
	v_ashrrev_i32_e32 v20, 7, v2
	v_add_u32_e32 v2, s16, v20
	v_mad_i64_i32 v[2:3], s[18:19], v2, s87, v[0:1]
	v_lshl_add_u64 v[2:3], v[2:3], 0, v[128:129]
	global_load_ushort v2, v[2:3], off offset:1536
	v_add_u32_e32 v3, 0x900, v48
	v_ashrrev_i32_e32 v3, 7, v3
	v_add_u32_e32 v21, s16, v3
	v_mad_i64_i32 v[0:1], s[18:19], v21, s87, v[0:1]
	v_lshl_add_u64 v[0:1], v[0:1], 0, v[128:129]
	global_load_ushort v0, v[0:1], off offset:1536
	s_movk_i32 s17, 0x110
	v_mul_lo_u32 v1, v5, s17
	v_mul_lo_u32 v5, v6, s17
	v_add3_u32 v1, s47, v1, v128
	v_add3_u32 v5, s47, v5, v128
	v_bfe_u32 v49, v48, 5, 1
	v_and_b32_e32 v52, 0xffffffdf, v48
	v_ashrrev_i32_e32 v53, 31, v52
	v_cmp_eq_u32_e32 vcc, 0, v49
	s_waitcnt vmcnt(9)
	v_lshlrev_b32_e32 v4, 16, v4
	v_mul_f32_e32 v4, 0xbfb8aa3b, v4
	v_exp_f32_e32 v4, v4
	s_waitcnt vmcnt(8)
	v_lshlrev_b32_e32 v6, 16, v7
	v_mul_f32_e32 v6, 0xbfb8aa3b, v6
	v_exp_f32_e32 v6, v6
	v_add_f32_e32 v4, 1.0, v4
	v_rcp_f32_e32 v4, v4
	v_add_f32_e32 v6, 1.0, v6
	s_waitcnt vmcnt(7)
	v_lshlrev_b32_e32 v7, 16, v9
	v_mul_f32_e32 v7, 0xbfb8aa3b, v7
	v_exp_f32_e32 v7, v7
	v_rcp_f32_e32 v6, v6
	v_cvt_pk_bf16_f32 v4, v4, s0
	ds_write_b16 v1, v4
	v_add_f32_e32 v7, 1.0, v7
	s_waitcnt vmcnt(6)
	v_lshlrev_b32_e32 v4, 16, v11
	v_cvt_pk_bf16_f32 v1, v6, s0
	v_mul_f32_e32 v4, 0xbfb8aa3b, v4
	ds_write_b16 v5, v1
	v_rcp_f32_e32 v1, v7
	v_exp_f32_e32 v4, v4
	v_mul_lo_u32 v5, v8, s17
	s_waitcnt vmcnt(5)
	v_lshlrev_b32_e32 v6, 16, v13
	v_mul_f32_e32 v6, 0xbfb8aa3b, v6
	v_exp_f32_e32 v6, v6
	v_cvt_pk_bf16_f32 v1, v1, s0
	v_add3_u32 v5, s47, v5, v128
	v_add_f32_e32 v4, 1.0, v4
	v_rcp_f32_e32 v4, v4
	ds_write_b16 v5, v1
	v_add_f32_e32 v5, 1.0, v6
	s_waitcnt vmcnt(4)
	v_lshlrev_b32_e32 v6, 16, v15
	v_mul_f32_e32 v6, 0xbfb8aa3b, v6
	v_exp_f32_e32 v6, v6
	v_cvt_pk_bf16_f32 v1, v4, s0
	v_mul_lo_u32 v4, v10, s17
	v_rcp_f32_e32 v5, v5
	v_add3_u32 v4, s47, v4, v128
	ds_write_b16 v4, v1
	v_add_f32_e32 v4, 1.0, v6
	v_rcp_f32_e32 v4, v4
	v_cvt_pk_bf16_f32 v1, v5, s0
	v_mul_lo_u32 v5, v12, s17
	v_add3_u32 v5, s47, v5, v128
	ds_write_b16 v5, v1
	v_cvt_pk_bf16_f32 v1, v4, s0
	s_waitcnt vmcnt(3)
	v_lshlrev_b32_e32 v4, 16, v17
	v_mul_f32_e32 v4, 0xbfb8aa3b, v4
	v_exp_f32_e32 v4, v4
	v_mul_lo_u32 v5, v14, s17
	v_add3_u32 v5, s47, v5, v128
	ds_write_b16 v5, v1
	v_add_f32_e32 v1, 1.0, v4
	s_waitcnt vmcnt(2)
	v_lshlrev_b32_e32 v4, 16, v19
	v_mul_f32_e32 v4, 0xbfb8aa3b, v4
	v_exp_f32_e32 v4, v4
	s_waitcnt vmcnt(1)
	v_lshlrev_b32_e32 v2, 16, v2
	v_mul_f32_e32 v2, 0xbfb8aa3b, v2
	v_exp_f32_e32 v2, v2
	s_waitcnt vmcnt(0)
	v_lshlrev_b32_e32 v0, 16, v0
	v_rcp_f32_e32 v1, v1
	v_add_f32_e32 v4, 1.0, v4
	v_mul_f32_e32 v0, 0xbfb8aa3b, v0
	v_rcp_f32_e32 v4, v4
	v_exp_f32_e32 v0, v0
	v_add_f32_e32 v2, 1.0, v2
	v_mul_lo_u32 v5, v16, s17
	v_rcp_f32_e32 v2, v2
	v_cvt_pk_bf16_f32 v1, v1, s0
	v_add3_u32 v5, s47, v5, v128
	ds_write_b16 v5, v1
	v_cvt_pk_bf16_f32 v1, v4, s0
	v_mul_lo_u32 v4, v18, s17
	v_add_f32_e32 v0, 1.0, v0
	v_add3_u32 v4, s47, v4, v128
	v_rcp_f32_e32 v0, v0
	ds_write_b16 v4, v1
	v_cvt_pk_bf16_f32 v1, v2, s0
	v_mul_lo_u32 v2, v20, s17
	v_add3_u32 v2, s47, v2, v128
	ds_write_b16 v2, v1
	v_mul_lo_u32 v1, v3, s17
	v_cvt_pk_bf16_f32 v0, v0, s0
	v_add3_u32 v1, s47, v1, v128
	v_lshlrev_b32_e32 v128, 4, v49
	ds_write_b16 v1, v0
	v_lshl_add_u64 v[50:51], s[4:5], 0, v[128:129]
	v_lshlrev_b64 v[0:1], 8, v[52:53]
	v_lshl_add_u64 v[4:5], v[50:51], 0, v[0:1]
	s_waitcnt lgkmcnt(0)
	s_barrier
	global_load_dwordx4 v[0:3], v[4:5], off
	global_load_dwordx4 v[16:19], v[4:5], off offset:32
	global_load_dwordx4 v[20:23], v[4:5], off offset:64
	global_load_dwordx4 v[24:27], v[4:5], off offset:96
	global_load_dwordx4 v[54:57], v[4:5], off offset:128
	global_load_dwordx4 v[58:61], v[4:5], off offset:160
	global_load_dwordx4 v[62:65], v[4:5], off offset:192
	global_load_dwordx4 v[66:69], v[4:5], off offset:224
	s_mov_b64 s[18:19], 0x2000
	v_lshl_add_u64 v[232:233], v[4:5], 0, s[18:19]
	global_load_dwordx4 v[200:203], v[232:233], off
	global_load_dwordx4 v[204:207], v[232:233], off offset:32
	global_load_dwordx4 v[208:211], v[232:233], off offset:64
	global_load_dwordx4 v[212:215], v[232:233], off offset:96
	global_load_dwordx4 v[216:219], v[232:233], off offset:128
	global_load_dwordx4 v[220:223], v[232:233], off offset:160
	global_load_dwordx4 v[224:227], v[232:233], off offset:192
	global_load_dwordx4 v[228:231], v[232:233], off offset:224
	v_and_b32_e32 v6, 31, v48
	v_mul_u32_u24_e32 v6, 0x110, v6
	v_add3_u32 v53, s47, v6, v128
	ds_read_b128 v[40:43], v53
	ds_read_b128 v[44:47], v53 offset:32
	ds_read_b128 v[36:39], v53 offset:64
	ds_read_b128 v[32:35], v53 offset:96
	ds_read_b128 v[28:31], v53 offset:128
	v_lshl_add_u32 v49, v49, 12, s47
	s_waitcnt vmcnt(15) lgkmcnt(4)
	v_mfma_f32_32x32x16_bf16 v[0:15], v[40:43], v[0:3], 0
	s_waitcnt vmcnt(14) lgkmcnt(3)
	v_mfma_f32_32x32x16_bf16 v[0:15], v[44:47], v[16:19], v[0:15]
	ds_read_b128 v[16:19], v53 offset:224
	s_waitcnt vmcnt(13) lgkmcnt(3)
	v_mfma_f32_32x32x16_bf16 v[0:15], v[36:39], v[20:23], v[0:15]
	ds_read_b128 v[20:23], v53 offset:192
	s_waitcnt vmcnt(12) lgkmcnt(3)
	v_mfma_f32_32x32x16_bf16 v[0:15], v[32:35], v[24:27], v[0:15]
	ds_read_b128 v[24:27], v53 offset:160
	s_waitcnt vmcnt(11) lgkmcnt(3)
	v_mfma_f32_32x32x16_bf16 v[0:15], v[28:31], v[54:57], v[0:15]
	s_waitcnt vmcnt(10) lgkmcnt(0)
	v_mfma_f32_32x32x16_bf16 v[0:15], v[24:27], v[58:61], v[0:15]
	s_waitcnt vmcnt(9)
	v_mfma_f32_32x32x16_bf16 v[0:15], v[20:23], v[62:65], v[0:15]
	s_waitcnt vmcnt(8)
	v_mfma_f32_32x32x16_bf16 v[0:15], v[16:19], v[66:69], v[0:15]
	s_nop 11
	v_lshl_add_u32 v12, v52, 2, v49
	ds_write2st64_b32 v12, v0, v1 offset0:34 offset1:38
	ds_write2st64_b32 v12, v2, v3 offset0:42 offset1:46
	ds_write2st64_b32 v12, v4, v5 offset0:66 offset1:70
	ds_write2st64_b32 v12, v6, v7 offset0:74 offset1:78
	s_and_saveexec_b64 s[18:19], vcc
	s_cbranch_execz .LBB0_222
	v_lshl_add_u32 v0, v52, 2, s47
	ds_write2st64_b32 v0, v8, v9 offset0:98 offset1:102
	ds_write2st64_b32 v0, v10, v11 offset0:106 offset1:110
.LBB0_222:
	s_or_b64 exec, exec, s[18:19]
	v_or_b32_e32 v52, 32, v48
	v_ashrrev_i32_e32 v53, 31, v52
	v_lshlrev_b64 v[0:1], 8, v[52:53]
	v_lshl_add_u64 v[50:51], v[50:51], 0, v[0:1]
	s_waitcnt vmcnt(7)
	v_mfma_f32_32x32x16_bf16 v[0:15], v[40:43], v[200:203], 0
	s_waitcnt vmcnt(6)
	v_mfma_f32_32x32x16_bf16 v[0:15], v[44:47], v[204:207], v[0:15]
	s_waitcnt vmcnt(5)
	v_mfma_f32_32x32x16_bf16 v[0:15], v[36:39], v[208:211], v[0:15]
	s_waitcnt vmcnt(4)
	v_mfma_f32_32x32x16_bf16 v[0:15], v[32:35], v[212:215], v[0:15]
	s_waitcnt vmcnt(3)
	v_mfma_f32_32x32x16_bf16 v[0:15], v[28:31], v[216:219], v[0:15]
	s_waitcnt vmcnt(2)
	v_mfma_f32_32x32x16_bf16 v[0:15], v[24:27], v[220:223], v[0:15]
	s_waitcnt vmcnt(1)
	v_mfma_f32_32x32x16_bf16 v[0:15], v[20:23], v[224:227], v[0:15]
	s_waitcnt vmcnt(0)
	v_mfma_f32_32x32x16_bf16 v[0:15], v[16:19], v[228:231], v[0:15]
	s_nop 11
	v_lshl_add_u32 v12, v52, 2, v49
	ds_write2st64_b32 v12, v0, v1 offset0:34 offset1:38
	ds_write2st64_b32 v12, v2, v3 offset0:42 offset1:46
	ds_write2st64_b32 v12, v4, v5 offset0:66 offset1:70
	ds_write2st64_b32 v12, v6, v7 offset0:74 offset1:78
	s_and_saveexec_b64 s[18:19], vcc
	s_cbranch_execz .LBB0_219
	v_lshl_add_u32 v0, v52, 2, s47
	ds_write2st64_b32 v0, v8, v9 offset0:98 offset1:102
	ds_write2st64_b32 v0, v10, v11 offset0:106 offset1:110
	s_branch .LBB0_219
